# G1e unit-order rotation for silu-tile load balance + epilogue-start vmcnt(0)->vmcnt(8) in 3 GEMMs
# speedup vs baseline: 1.0026x; 1.0026x over previous
; __device__ __forceinline__ f32x2 gelu_pk(f32x2 v) {
;     const f32x2 av = __builtin_elementwise_abs(v), d = av * 0.2316418882f + 1.0f;
;     f32x2 t; t.x = __builtin_amdgcn_rcpf(d.x); t.y = __builtin_amdgcn_rcpf(d.y);
;     f32x2 q = t * 0.5307027145f + (-0.7265760135f); q = q * t + 0.7107068705f; q = q * t + (-0.142248368f); q = q * t + 0.127414796f; q = q * t;
;     const f32x2 s = (v * v) * (-0.72134752044f);
;     f32x2 e; e.x = __builtin_amdgcn_exp2f(s.x); e.y = __builtin_amdgcn_exp2f(s.y);
;     const f32x2 m = v * (q * e), r = v - m;
;     f32x2 o; o.x = v.x < 0.f ? m.x : r.x; o.y = v.y < 0.f ? m.y : r.y; return o;
; }
; __device__ __forceinline__ float ss2f(unsigned long long v) { return (float)v * (1.0f / 16777216.0f); }
; __device__ __forceinline__ unsigned long long f2ss(float v) { return (unsigned long long)(v * 16777216.0f); }
; __device__ __forceinline__ void prefetch_ss(PreSS& p, const unsigned long long* ss, const Unit& u, int wr, int fr, int fq) {
;     const int k0 = 2 * fq, k1 = 2 * fq + 1, base = u.pm * BM + wr * 64 + fr;
;     p.v0 = *(const __attribute__((address_space(1))) unsigned long long*)(ss + base + (k0 >> 2) * HALF + (k0 & 3) * 16);
;     p.v1 = *(const __attribute__((address_space(1))) unsigned long long*)(ss + base + (k1 >> 2) * HALF + (k1 & 3) * 16);
; }
; __device__ __forceinline__ void rstd8(float (&r)[8], const PreSS& p, int fr) {
;     const float a = __builtin_amdgcn_rsqf(ss2f(p.v0) * (1.0f / 1024.0f) + RMS_EPS), b = __builtin_amdgcn_rsqf(ss2f(p.v1) * (1.0f / 1024.0f) + RMS_EPS);
; #pragma unroll
;     for (int k = 0; k < 8; ++k) r[k] = __shfl((k & 1) ? b : a, fr + 16 * (k >> 1));
; }
;     __device__ __forceinline__ void operator()(const f32x4 (&acc)[2][2][4][2], const Unit& u, int wr, int wc, int fr, int fq, const Pre& pre) const {
;         const int row0 = u.pm * BM + wr * 64 + fr, col0 = u.pn * BM + wc * 32 + 8 * fq;
;         float rs8[8]; rstd8(rs8, pre, fr);
;         const bool isv = u.pn >= 4;
; #pragma unroll
;         for (int ai = 0; ai < 2; ++ai)
; #pragma unroll
;             for (int m = 0; m < 4; ++m) { const int row = row0 + ai * HALF + m * 16; const float r = rs8[ai * 4 + m];
;                 bf16_t* rowp = O + (size_t)row * 2048 + col0; float sq = 0.f;
; #pragma unroll
;                 for (int bj = 0; bj < 2; ++bj) { f32x4 v0 = acc[ai][bj][m][0] * r, v1 = acc[ai][bj][m][1] * r;
.LBB0_57:
	s_waitcnt vmcnt(8)
	v_ffbh_u32_e32 v154, v153
	v_min_u32_e32 v154, 32, v154
	v_lshlrev_b64 v[152:153], v154, v[152:153]
	v_min_u32_e32 v152, 1, v152
	v_or_b32_e32 v152, v153, v152
	v_cvt_f32_u32_e32 v152, v152
	v_sub_u32_e32 v153, 32, v154
	s_mov_b32 s8, 0x3e6d3388
	s_cmp_gt_i32 s4, 3
	v_ldexp_f32 v152, v152, v153
	v_ffbh_u32_e32 v153, v147
	v_min_u32_e32 v153, 32, v153
	v_lshlrev_b64 v[146:147], v153, v[146:147]
	v_min_u32_e32 v146, 1, v146
	v_or_b32_e32 v146, v147, v146
	v_cvt_f32_u32_e32 v146, v146
	v_mul_f32_e32 v152, 0x33800000, v152
	v_fmamk_f32 v152, v152, 0x3a800000, v233
	v_rsq_f32_e32 v152, v152
	v_sub_u32_e32 v147, 32, v153
	v_ldexp_f32 v146, v146, v147
	v_and_b32_e32 v147, 64, v236
	v_or_b32_e32 v153, v147, v145
	v_lshlrev_b32_e32 v153, 2, v153
	ds_bpermute_b32 v168, v153, v152
	v_mul_f32_e32 v146, 0x33800000, v146
	v_fmamk_f32 v146, v146, 0x3a800000, v233
	v_rsq_f32_e32 v146, v146
	s_mov_b32 s12, 0xbf3a00e3
	s_waitcnt lgkmcnt(0)
	v_pk_mul_f32 v[124:125], v[124:125], v[168:169] op_sel_hi:[1,0]
	v_pk_mul_f32 v[170:171], v[120:121], v[168:169] op_sel_hi:[1,0]
	v_and_b32_e32 v121, 0x7fffffff, v125
	v_and_b32_e32 v120, 0x7fffffff, v124
	v_pk_fma_f32 v[120:121], v[120:121], s[8:9], 1.0 op_sel_hi:[1,0,0]
	v_lshl_or_b32 v162, s4, 8, v159
	v_rcp_f32_e32 v172, v120
	v_rcp_f32_e32 v173, v121
	s_cselect_b64 s[64:65], -1, 0
	s_cmp_lt_i32 s4, 4
	v_mov_b64_e32 v[120:121], s[12:13]
	s_mov_b32 s10, 0x3f07dc22
	v_pk_mul_f32 v[176:177], v[124:125], v[124:125]
	s_mov_b32 s4, 0xbf38aa3b
	v_pk_fma_f32 v[174:175], v[172:173], s[10:11], v[120:121] op_sel_hi:[1,0,0]
	s_mov_b32 s14, 0x3f35f0e3
	v_pk_mul_f32 v[176:177], v[176:177], s[4:5] op_sel_hi:[1,0]
	v_pk_fma_f32 v[174:175], v[172:173], v[174:175], s[14:15] op_sel_hi:[1,1,0]
	s_mov_b32 s36, 0xbe11a98e
	v_exp_f32_e32 v176, v176
	v_exp_f32_e32 v177, v177
	ds_bpermute_b32 v166, v153, v146
	ds_bpermute_b32 v164, v153, v152 offset:64
	ds_bpermute_b32 v160, v153, v146 offset:64
	ds_bpermute_b32 v158, v153, v152 offset:128
	ds_bpermute_b32 v156, v153, v146 offset:128
	ds_bpermute_b32 v154, v153, v152 offset:192
	ds_bpermute_b32 v146, v153, v146 offset:192
	v_xor_b32_e32 v152, 16, v236
	v_add_u32_e32 v153, 64, v147
	v_pk_fma_f32 v[174:175], v[172:173], v[174:175], s[36:37] op_sel_hi:[1,1,0]
	s_mov_b32 s66, 0x3e027906
	v_cmp_lt_i32_e32 vcc, v152, v153
	v_pk_fma_f32 v[174:175], v[172:173], v[174:175], s[66:67] op_sel_hi:[1,1,0]
	v_pk_mul_f32 v[126:127], v[126:127], v[168:169] op_sel_hi:[1,0]
	v_cndmask_b32_e32 v147, v236, v152, vcc
	v_xor_b32_e32 v152, 32, v236
	v_pk_mul_f32 v[172:173], v[172:173], v[174:175]
	v_cmp_lt_i32_e32 vcc, v152, v153
	v_pk_mul_f32 v[172:173], v[176:177], v[172:173]
	v_pk_mul_f32 v[174:175], v[126:127], v[126:127]
	v_cndmask_b32_e32 v152, v236, v152, vcc
	v_pk_mul_f32 v[176:177], v[124:125], v[172:173]
	v_pk_fma_f32 v[172:173], v[124:125], v[172:173], v[124:125] neg_lo:[1,0,0] neg_hi:[1,0,0]
	v_cmp_gt_f32_e32 vcc, 0, v124
	v_pk_mul_f32 v[174:175], v[174:175], s[4:5] op_sel_hi:[1,0]
	v_pk_mul_f32 v[122:123], v[122:123], v[168:169] op_sel_hi:[1,0]
	v_cndmask_b32_e32 v124, v172, v176, vcc
	v_cmp_gt_f32_e32 vcc, 0, v125
	v_and_b32_e32 v172, 0x7fffffff, v126
	v_exp_f32_e32 v174, v174
	v_cndmask_b32_e32 v125, v173, v177, vcc
	v_and_b32_e32 v173, 0x7fffffff, v127
	v_pk_fma_f32 v[172:173], v[172:173], s[8:9], 1.0 op_sel_hi:[1,0,0]
	v_exp_f32_e32 v175, v175
	v_rcp_f32_e32 v172, v172
	v_rcp_f32_e32 v173, v173
	v_cmp_gt_f32_e32 vcc, 0, v126
	v_lshlrev_b32_e32 v165, 2, v152
	v_lshlrev_b64 v[152:153], 12, v[142:143]
	v_pk_fma_f32 v[176:177], v[172:173], s[10:11], v[120:121] op_sel_hi:[1,0,0]
	v_ashrrev_i32_e32 v163, 31, v162
	v_pk_fma_f32 v[176:177], v[172:173], v[176:177], s[14:15] op_sel_hi:[1,1,0]
	v_lshl_add_u64 v[152:153], s[30:31], 0, v[152:153]
	v_pk_fma_f32 v[176:177], v[172:173], v[176:177], s[36:37] op_sel_hi:[1,1,0]
	v_lshl_add_u64 v[152:153], v[162:163], 1, v[152:153]
	v_pk_fma_f32 v[176:177], v[172:173], v[176:177], s[66:67] op_sel_hi:[1,1,0]
	v_lshlrev_b32_e32 v147, 2, v147
	v_pk_mul_f32 v[172:173], v[172:173], v[176:177]
	v_pk_mul_f32 v[176:177], v[170:171], v[170:171]
	v_pk_mul_f32 v[172:173], v[174:175], v[172:173]
	v_pk_mul_f32 v[176:177], v[176:177], s[4:5] op_sel_hi:[1,0]
	v_pk_mul_f32 v[174:175], v[126:127], v[172:173]
	v_pk_fma_f32 v[172:173], v[126:127], v[172:173], v[126:127] neg_lo:[1,0,0] neg_hi:[1,0,0]
	v_exp_f32_e32 v176, v176
	v_cndmask_b32_e32 v126, v172, v174, vcc
	v_cmp_gt_f32_e32 vcc, 0, v127
	v_and_b32_e32 v172, 0x7fffffff, v170
	v_exp_f32_e32 v177, v177
	v_cndmask_b32_e32 v127, v173, v175, vcc
	v_and_b32_e32 v173, 0x7fffffff, v171
	v_pk_fma_f32 v[172:173], v[172:173], s[8:9], 1.0 op_sel_hi:[1,0,0]
	v_cmp_gt_f32_e32 vcc, 0, v170
	v_rcp_f32_e32 v172, v172
	v_rcp_f32_e32 v173, v173
	v_readlane_b32 s76, v255, 14
	v_readlane_b32 s77, v255, 15
	v_pk_fma_f32 v[174:175], v[172:173], s[10:11], v[120:121] op_sel_hi:[1,0,0]
	s_nop 0
	v_pk_fma_f32 v[174:175], v[172:173], v[174:175], s[14:15] op_sel_hi:[1,1,0]
	s_nop 0
	v_pk_fma_f32 v[174:175], v[172:173], v[174:175], s[36:37] op_sel_hi:[1,1,0]
	s_nop 0
	v_pk_fma_f32 v[174:175], v[172:173], v[174:175], s[66:67] op_sel_hi:[1,1,0]
	s_nop 0
	v_pk_mul_f32 v[172:173], v[172:173], v[174:175]
	v_pk_mul_f32 v[174:175], v[122:123], v[122:123]
	v_pk_mul_f32 v[172:173], v[176:177], v[172:173]
	s_nop 0
	v_pk_mul_f32 v[176:177], v[170:171], v[172:173]
	v_pk_fma_f32 v[172:173], v[170:171], v[172:173], v[170:171] neg_lo:[1,0,0] neg_hi:[1,0,0]
	v_and_b32_e32 v170, 0x7fffffff, v122
	v_cndmask_b32_e32 v167, v172, v176, vcc
	v_cmp_gt_f32_e32 vcc, 0, v171
	v_and_b32_e32 v171, 0x7fffffff, v123
	v_pk_fma_f32 v[170:171], v[170:171], s[8:9], 1.0 op_sel_hi:[1,0,0]
; __device__ __forceinline__ unsigned long long f2ss(float v) { return (unsigned long long)(v * 16777216.0f); }
; __device__ __forceinline__ u32x4 pack8(f32x4 v0, f32x4 v1) { u32x4 w; w.x = cvt_pk_bf16(v0[0], v0[1]); w.y = cvt_pk_bf16(v0[2], v0[3]); w.z = cvt_pk_bf16(v1[0], v1[1]); w.w = cvt_pk_bf16(v1[2], v1[3]); return w; }
; __device__ __forceinline__ f32x2 gelu_pk(f32x2 v) {
;     const f32x2 av = __builtin_elementwise_abs(v), d = av * 0.2316418882f + 1.0f;
;     f32x2 t; t.x = __builtin_amdgcn_rcpf(d.x); t.y = __builtin_amdgcn_rcpf(d.y);
;     f32x2 q = t * 0.5307027145f + (-0.7265760135f); q = q * t + 0.7107068705f; q = q * t + (-0.142248368f); q = q * t + 0.127414796f; q = q * t;
;     const f32x2 s = (v * v) * (-0.72134752044f);
;     f32x2 e; e.x = __builtin_amdgcn_exp2f(s.x); e.y = __builtin_amdgcn_exp2f(s.y);
;     const f32x2 m = v * (q * e), r = v - m;
;     f32x2 o; o.x = v.x < 0.f ? m.x : r.x; o.y = v.y < 0.f ? m.y : r.y; return o;
; }
;     __device__ __forceinline__ void operator()(const f32x4 (&acc)[2][2][4][2], const Unit& u, int wr, int wc, int fr, int fq, const Pre& pre) const {
;     ...
;             for (int m = 0; m < 4; ++m) { const int row = row0 + ai * HALF + m * 16; const float r = rs8[ai * 4 + m];
;                 bf16_t* rowp = O + (size_t)row * 2048 + col0; float sq = 0.f;
; #pragma unroll
;                 for (int bj = 0; bj < 2; ++bj) { f32x4 v0 = acc[ai][bj][m][0] * r, v1 = acc[ai][bj][m][1] * r;
;                     f32x2 a = gelu_pk((f32x2){v0[0], v0[1]}), b = gelu_pk((f32x2){v0[2], v0[3]}), c = gelu_pk((f32x2){v1[0], v1[1]}), d = gelu_pk((f32x2){v1[2], v1[3]});
;                     v0 = (f32x4){a.x, a.y, b.x, b.y}; v1 = (f32x4){c.x, c.y, d.x, d.y};
;                     sq += (v0[0] * v0[0] + v0[1] * v0[1]) + (v0[2] * v0[2] + v0[3] * v0[3]) + (v1[0] * v1[0] + v1[1] * v1[1]) + (v1[2] * v1[2] + v1[3] * v1[3]);
;                     *(u32x4*)(rowp + bj * HALF) = pack8(v0, v1); }
;                 if (isv) { sq += __shfl_xor(sq, 16); sq += __shfl_xor(sq, 32); if (fq == 0) atomicAdd(vss + row, f2ss(sq)); } }
	v_cndmask_b32_e32 v169, v173, v177, vcc
	v_rcp_f32_e32 v170, v170
	v_rcp_f32_e32 v171, v171
	v_cmp_gt_f32_e32 vcc, 0, v122
	v_pk_mul_f32 v[116:117], v[116:117], v[168:169] op_sel_hi:[1,0]
	v_pk_mul_f32 v[118:119], v[118:119], v[168:169] op_sel_hi:[1,0]
	v_pk_fma_f32 v[172:173], v[170:171], s[10:11], v[120:121] op_sel_hi:[1,0,0]
	v_pk_mul_f32 v[114:115], v[114:115], v[168:169] op_sel_hi:[1,0]
	v_pk_fma_f32 v[172:173], v[170:171], v[172:173], s[14:15] op_sel_hi:[1,1,0]
	s_nop 0
	v_pk_fma_f32 v[172:173], v[170:171], v[172:173], s[36:37] op_sel_hi:[1,1,0]
	s_nop 0
	v_pk_fma_f32 v[172:173], v[170:171], v[172:173], s[66:67] op_sel_hi:[1,1,0]
	s_nop 0
	v_pk_mul_f32 v[170:171], v[170:171], v[172:173]
	v_pk_mul_f32 v[172:173], v[174:175], s[4:5] op_sel_hi:[1,0]
	v_pk_mul_f32 v[174:175], v[116:117], v[116:117]
	v_exp_f32_e32 v172, v172
	v_exp_f32_e32 v173, v173
	v_pk_mul_f32 v[174:175], v[174:175], s[4:5] op_sel_hi:[1,0]
	v_pk_mul_f32 v[170:171], v[172:173], v[170:171]
	s_nop 0
	v_pk_mul_f32 v[172:173], v[122:123], v[170:171]
	v_pk_fma_f32 v[170:171], v[122:123], v[170:171], v[122:123] neg_lo:[1,0,0] neg_hi:[1,0,0]
	v_exp_f32_e32 v174, v174
	v_cndmask_b32_e32 v122, v170, v172, vcc
	v_cmp_gt_f32_e32 vcc, 0, v123
	v_cvt_pk_bf16_f32 v170, v124, v125
	v_exp_f32_e32 v175, v175
	s_nop 0
	v_cndmask_b32_e32 v123, v171, v173, vcc
	v_cvt_pk_bf16_f32 v171, v126, v127
	v_cvt_pk_bf16_f32 v172, v167, v169
	v_cvt_pk_bf16_f32 v173, v122, v123
	flat_store_dwordx4 v[152:153], v[170:173]
	v_cmp_gt_f32_e32 vcc, 0, v116
	s_nop 0
	v_pk_mul_f32 v[170:171], v[112:113], v[168:169] op_sel_hi:[1,0]
	v_and_b32_e32 v113, 0x7fffffff, v117
	v_and_b32_e32 v112, 0x7fffffff, v116
	v_pk_fma_f32 v[112:113], v[112:113], s[8:9], 1.0 op_sel_hi:[1,0,0]
	s_nop 0
	v_rcp_f32_e32 v112, v112
	v_rcp_f32_e32 v113, v113
	s_nop 0
	v_pk_fma_f32 v[172:173], v[112:113], s[10:11], v[120:121] op_sel_hi:[1,0,0]
	s_nop 0
	v_pk_fma_f32 v[172:173], v[112:113], v[172:173], s[14:15] op_sel_hi:[1,1,0]
	s_nop 0
	v_pk_fma_f32 v[172:173], v[112:113], v[172:173], s[36:37] op_sel_hi:[1,1,0]
	s_nop 0
	v_pk_fma_f32 v[172:173], v[112:113], v[172:173], s[66:67] op_sel_hi:[1,1,0]
	s_nop 0
	v_pk_mul_f32 v[112:113], v[112:113], v[172:173]
	v_pk_mul_f32 v[172:173], v[118:119], v[118:119]
	v_pk_mul_f32 v[112:113], v[174:175], v[112:113]
	v_pk_mul_f32 v[172:173], v[172:173], s[4:5] op_sel_hi:[1,0]
	v_pk_mul_f32 v[174:175], v[116:117], v[112:113]
	v_pk_fma_f32 v[112:113], v[116:117], v[112:113], v[116:117] neg_lo:[1,0,0] neg_hi:[1,0,0]
	v_and_b32_e32 v116, 0x7fffffff, v118
	v_cndmask_b32_e32 v112, v112, v174, vcc
	v_cmp_gt_f32_e32 vcc, 0, v117
	v_and_b32_e32 v117, 0x7fffffff, v119
	v_pk_fma_f32 v[116:117], v[116:117], s[8:9], 1.0 op_sel_hi:[1,0,0]
	v_cndmask_b32_e32 v113, v113, v175, vcc
	v_rcp_f32_e32 v116, v116
	v_rcp_f32_e32 v117, v117
	v_exp_f32_e32 v172, v172
	v_exp_f32_e32 v173, v173
	v_cmp_gt_f32_e32 vcc, 0, v118
	v_pk_fma_f32 v[174:175], v[116:117], s[10:11], v[120:121] op_sel_hi:[1,0,0]
	s_nop 0
	v_pk_fma_f32 v[174:175], v[116:117], v[174:175], s[14:15] op_sel_hi:[1,1,0]
	s_nop 0
	v_pk_fma_f32 v[174:175], v[116:117], v[174:175], s[36:37] op_sel_hi:[1,1,0]
	s_nop 0
	v_pk_fma_f32 v[174:175], v[116:117], v[174:175], s[66:67] op_sel_hi:[1,1,0]
	s_nop 0
	v_pk_mul_f32 v[116:117], v[116:117], v[174:175]
	v_pk_mul_f32 v[174:175], v[170:171], v[170:171]
	v_pk_mul_f32 v[116:117], v[172:173], v[116:117]
	v_pk_mul_f32 v[174:175], v[174:175], s[4:5] op_sel_hi:[1,0]
	v_pk_mul_f32 v[172:173], v[118:119], v[116:117]
	v_pk_fma_f32 v[116:117], v[118:119], v[116:117], v[118:119] neg_lo:[1,0,0] neg_hi:[1,0,0]
	v_and_b32_e32 v118, 0x7fffffff, v170
	v_cndmask_b32_e32 v116, v116, v172, vcc
	v_cmp_gt_f32_e32 vcc, 0, v119
	v_and_b32_e32 v119, 0x7fffffff, v171
	v_pk_fma_f32 v[118:119], v[118:119], s[8:9], 1.0 op_sel_hi:[1,0,0]
	v_cndmask_b32_e32 v117, v117, v173, vcc
	v_rcp_f32_e32 v118, v118
	v_rcp_f32_e32 v119, v119
	v_exp_f32_e32 v174, v174
	v_exp_f32_e32 v175, v175
	v_cmp_gt_f32_e32 vcc, 0, v170
	v_pk_fma_f32 v[172:173], v[118:119], s[10:11], v[120:121] op_sel_hi:[1,0,0]
	s_nop 0
	v_pk_fma_f32 v[172:173], v[118:119], v[172:173], s[14:15] op_sel_hi:[1,1,0]
	s_nop 0
	v_pk_fma_f32 v[172:173], v[118:119], v[172:173], s[36:37] op_sel_hi:[1,1,0]
	s_nop 0
	v_pk_fma_f32 v[172:173], v[118:119], v[172:173], s[66:67] op_sel_hi:[1,1,0]
	s_nop 0
	v_pk_mul_f32 v[118:119], v[118:119], v[172:173]
	v_pk_mul_f32 v[172:173], v[114:115], v[114:115]
	v_pk_mul_f32 v[118:119], v[174:175], v[118:119]
	s_nop 0
	v_pk_mul_f32 v[174:175], v[170:171], v[118:119]
	v_pk_fma_f32 v[118:119], v[170:171], v[118:119], v[170:171] neg_lo:[1,0,0] neg_hi:[1,0,0]
	v_and_b32_e32 v170, 0x7fffffff, v114
	v_cndmask_b32_e32 v118, v118, v174, vcc
	v_cmp_gt_f32_e32 vcc, 0, v171
	v_and_b32_e32 v171, 0x7fffffff, v115
	v_pk_fma_f32 v[170:171], v[170:171], s[8:9], 1.0 op_sel_hi:[1,0,0]
	v_cndmask_b32_e32 v119, v119, v175, vcc
	v_rcp_f32_e32 v170, v170
	v_rcp_f32_e32 v171, v171
	v_cmp_gt_f32_e32 vcc, 0, v114
	v_pk_fma_f32 v[120:121], v[170:171], s[10:11], v[120:121] op_sel_hi:[1,0,0]
	s_nop 0
	v_pk_fma_f32 v[120:121], v[170:171], v[120:121], s[14:15] op_sel_hi:[1,1,0]
	s_nop 0
	v_pk_fma_f32 v[120:121], v[170:171], v[120:121], s[36:37] op_sel_hi:[1,1,0]
	s_nop 0
	v_pk_fma_f32 v[120:121], v[170:171], v[120:121], s[66:67] op_sel_hi:[1,1,0]
	s_nop 0
	v_pk_mul_f32 v[120:121], v[170:171], v[120:121]
	v_pk_mul_f32 v[170:171], v[172:173], s[4:5] op_sel_hi:[1,0]
	s_nop 0
	v_exp_f32_e32 v170, v170
	v_exp_f32_e32 v171, v171
	s_nop 0
	v_pk_mul_f32 v[120:121], v[170:171], v[120:121]
	s_nop 0
	v_pk_mul_f32 v[170:171], v[114:115], v[120:121]
	v_pk_fma_f32 v[120:121], v[114:115], v[120:121], v[114:115] neg_lo:[1,0,0] neg_hi:[1,0,0]
	s_nop 0
	v_cndmask_b32_e32 v114, v120, v170, vcc
	v_cmp_gt_f32_e32 vcc, 0, v115
	v_cvt_pk_bf16_f32 v170, v112, v113
	s_nop 1
	v_cndmask_b32_e32 v115, v121, v171, vcc
	v_cvt_pk_bf16_f32 v171, v116, v117
	v_cvt_pk_bf16_f32 v172, v118, v119
	v_cvt_pk_bf16_f32 v173, v114, v115
	flat_store_dwordx4 v[152:153], v[170:173] offset:256
	s_cbranch_scc1 .LBB0_61
; __device__ __forceinline__ u32x4 pack8(f32x4 v0, f32x4 v1) { u32x4 w; w.x = cvt_pk_bf16(v0[0], v0[1]); w.y = cvt_pk_bf16(v0[2], v0[3]); w.z = cvt_pk_bf16(v1[0], v1[1]); w.w = cvt_pk_bf16(v1[2], v1[3]); return w; }
; __device__ __forceinline__ float ss2f(unsigned long long v) { return (float)v * (1.0f / 16777216.0f); }
; __device__ __forceinline__ unsigned long long f2ss(float v) { return (unsigned long long)(v * 16777216.0f); }
;     __device__ __forceinline__ void operator()(const f32x4 (&acc)[2][2][4][2], const Unit& u, int wr, int wc, int fr, int fq, const Pre& pre) const {
;     ...
;                     sq += (v0[0] * v0[0] + v0[1] * v0[1]) + (v0[2] * v0[2] + v0[3] * v0[3]) + (v1[0] * v1[0] + v1[1] * v1[1]) + (v1[2] * v1[2] + v1[3] * v1[3]);
;                     *(u32x4*)(rowp + bj * HALF) = pack8(v0, v1); }
;                 if (isv) { sq += __shfl_xor(sq, 16); sq += __shfl_xor(sq, 32); if (fq == 0) atomicAdd(vss + row, f2ss(sq)); } }
	v_mul_f32_e32 v120, v123, v123
	v_mul_f32_e32 v113, v113, v113
	v_fmac_f32_e32 v120, v122, v122
	v_mul_f32_e32 v121, v125, v125
	v_mul_f32_e32 v122, v127, v127
	v_fmac_f32_e32 v113, v112, v112
	v_mul_f32_e32 v112, v117, v117
	v_fmac_f32_e32 v121, v124, v124
	v_fmac_f32_e32 v122, v126, v126
	v_fmac_f32_e32 v112, v116, v116
	v_add_f32_e32 v121, v121, v122
	v_mul_f32_e32 v122, v169, v169
	v_add_f32_e32 v112, v113, v112
	v_mul_f32_e32 v113, v119, v119
	v_fmac_f32_e32 v122, v167, v167
	v_mul_f32_e32 v115, v115, v115
	v_fmac_f32_e32 v113, v118, v118
	v_add_f32_e32 v121, v122, v121
	v_fmac_f32_e32 v115, v114, v114
	v_add_f32_e32 v112, v113, v112
	v_add_f32_e32 v120, v120, v121
	v_add_f32_e32 v112, v115, v112
	v_add_f32_e32 v112, v120, v112
	ds_bpermute_b32 v113, v147, v112
	s_waitcnt lgkmcnt(0)
	v_add_f32_e32 v112, v112, v113
	ds_bpermute_b32 v113, v165, v112
	s_and_saveexec_b64 s[26:27], s[40:41]
	s_cbranch_execz .LBB0_60
	s_waitcnt lgkmcnt(0)
	v_add_f32_e32 v112, v112, v113
	v_mul_f32_e32 v112, 0x4b800000, v112
	v_trunc_f32_e32 v112, v112
	v_mul_f32_e32 v113, 0x2f800000, v112
	v_floor_f32_e32 v113, v113
	v_fmac_f32_e32 v112, 0xcf800000, v113
	v_cvt_u32_f32_e32 v112, v112
	v_cvt_u32_f32_e32 v113, v113
	v_lshl_add_u64 v[114:115], v[142:143], 3, s[52:53]
	flat_atomic_add_x2 v[114:115], v[112:113]

; __device__ __forceinline__ u32x4 pack8(f32x4 v0, f32x4 v1) { u32x4 w; w.x = cvt_pk_bf16(v0[0], v0[1]); w.y = cvt_pk_bf16(v0[2], v0[3]); w.z = cvt_pk_bf16(v1[0], v1[1]); w.w = cvt_pk_bf16(v1[2], v1[3]); return w; }
; __device__ __forceinline__ float silu1(float v) { return v * __builtin_amdgcn_rcpf(1.0f + __builtin_amdgcn_exp2f(-1.4426950408889634f * v)); }
; __device__ __forceinline__ f32x4 silu4(f32x4 v) { return (f32x4){silu1(v[0]), silu1(v[1]), silu1(v[2]), silu1(v[3])}; }
;     __device__ __forceinline__ void operator()(const f32x4 (&acc)[2][2][4][2], const Unit& u, int wr, int wc, int fr, int fq, const Pre& pre) const {
;         const int row0 = u.pm * BM + wr * 64 + fr, col0 = u.pn * HALF + wc * 32 + 8 * fq;
;         float rs8[8]; rstd8(rs8, pre, fr);
; #pragma unroll
;         for (int ai = 0; ai < 2; ++ai)
; #pragma unroll
;             for (int m = 0; m < 4; ++m) { const int row = row0 + ai * HALF + m * 16; const float r = rs8[ai * 4 + m];
;                 const f32x4 g0 = silu4(acc[ai][0][m][0] * r), g1 = silu4(acc[ai][0][m][1] * r);
;                 const f32x4 v0 = g0 * (acc[ai][1][m][0] * r), v1 = g1 * (acc[ai][1][m][1] * r);
;                 *(u32x4*)(O + (size_t)row * 2816 + col0) = pack8(v0, v1); }
.LBB0_155:
	s_waitcnt vmcnt(8)
	v_ffbh_u32_e32 v143, v153
	v_min_u32_e32 v143, 32, v143
	v_lshlrev_b64 v[152:153], v143, v[152:153]
	v_min_u32_e32 v152, 1, v152
	v_or_b32_e32 v152, v153, v152
	v_cvt_f32_u32_e32 v152, v152
	v_sub_u32_e32 v143, 32, v143
	v_lshl_or_b32 v164, s4, 7, v159
	v_ashrrev_i32_e32 v165, 31, v164
	v_ldexp_f32 v143, v152, v143
	v_ffbh_u32_e32 v152, v147
	v_min_u32_e32 v152, 32, v152
	v_lshlrev_b64 v[146:147], v152, v[146:147]
	v_min_u32_e32 v146, 1, v146
	v_or_b32_e32 v146, v147, v146
	v_mul_f32_e32 v143, 0x33800000, v143
	v_cvt_f32_u32_e32 v146, v146
	v_fmamk_f32 v143, v143, 0x3a800000, v233
	v_rsq_f32_e32 v143, v143
	v_sub_u32_e32 v147, 32, v152
	v_ldexp_f32 v146, v146, v147
	v_and_or_b32 v147, v236, 64, v145
	v_lshlrev_b32_e32 v147, 2, v147
	ds_bpermute_b32 v166, v147, v143
	ds_bpermute_b32 v160, v147, v143 offset:64
	ds_bpermute_b32 v156, v147, v143 offset:128
	ds_bpermute_b32 v152, v147, v143 offset:192
	v_mul_f32_e32 v146, 0x33800000, v146
	s_waitcnt lgkmcnt(3)
	v_pk_mul_f32 v[124:125], v[124:125], v[166:167] op_sel_hi:[1,0]
	v_pk_mul_f32 v[126:127], v[126:127], v[166:167] op_sel_hi:[1,0]
	v_mul_f32_e32 v143, 0xbfb8aa3b, v124
	v_exp_f32_e32 v143, v143
	v_pk_mul_f32 v[120:121], v[120:121], v[166:167] op_sel_hi:[1,0]
	v_pk_mul_f32 v[122:123], v[122:123], v[166:167] op_sel_hi:[1,0]
	v_fmamk_f32 v146, v146, 0x3a800000, v233
	v_add_f32_e32 v143, 1.0, v143
	v_rcp_f32_e32 v168, v143
	v_mul_f32_e32 v143, 0xbfb8aa3b, v125
	v_exp_f32_e32 v143, v143
	v_rsq_f32_e32 v146, v146
	v_pk_mul_f32 v[116:117], v[116:117], v[166:167] op_sel_hi:[1,0]
	v_pk_mul_f32 v[118:119], v[118:119], v[166:167] op_sel_hi:[1,0]
	v_add_f32_e32 v143, 1.0, v143
	v_rcp_f32_e32 v169, v143
	v_mul_f32_e32 v143, 0xbfb8aa3b, v126
	v_exp_f32_e32 v143, v143
	ds_bpermute_b32 v162, v147, v146
	v_pk_mul_f32 v[124:125], v[124:125], v[168:169]
	v_pk_mul_f32 v[112:113], v[112:113], v[166:167] op_sel_hi:[1,0]
	v_add_f32_e32 v143, 1.0, v143
	v_rcp_f32_e32 v170, v143
	v_mul_f32_e32 v143, 0xbfb8aa3b, v127
	v_exp_f32_e32 v143, v143
	v_pk_mul_f32 v[116:117], v[116:117], v[124:125]
	v_pk_mul_f32 v[114:115], v[114:115], v[166:167] op_sel_hi:[1,0]
	v_cvt_pk_bf16_f32 v116, v116, v117
	v_add_f32_e32 v143, 1.0, v143
	v_rcp_f32_e32 v171, v143
	v_mul_f32_e32 v143, 0xbfb8aa3b, v120
	v_exp_f32_e32 v143, v143
	s_movk_i32 s4, 0x1600
	v_pk_mul_f32 v[126:127], v[126:127], v[170:171]
	s_waitcnt lgkmcnt(0)
	v_pk_mul_f32 v[110:111], v[110:111], v[162:163] op_sel_hi:[1,0]
	v_add_f32_e32 v143, 1.0, v143
	v_rcp_f32_e32 v168, v143
	v_mul_f32_e32 v143, 0xbfb8aa3b, v121
	v_exp_f32_e32 v143, v143
	v_pk_mul_f32 v[118:119], v[118:119], v[126:127]
	v_pk_mul_f32 v[108:109], v[108:109], v[162:163] op_sel_hi:[1,0]
	v_cvt_pk_bf16_f32 v117, v118, v119
	v_add_f32_e32 v143, 1.0, v143
	v_rcp_f32_e32 v169, v143
	v_mul_f32_e32 v143, 0xbfb8aa3b, v122
	v_exp_f32_e32 v143, v143
	v_pk_mul_f32 v[106:107], v[106:107], v[162:163] op_sel_hi:[1,0]
	v_pk_mul_f32 v[120:121], v[120:121], v[168:169]
	v_pk_mul_f32 v[104:105], v[104:105], v[162:163] op_sel_hi:[1,0]
	v_add_f32_e32 v143, 1.0, v143
	v_rcp_f32_e32 v170, v143
	v_mul_f32_e32 v143, 0xbfb8aa3b, v123
	v_exp_f32_e32 v143, v143
	v_pk_mul_f32 v[112:113], v[112:113], v[120:121]
	v_pk_mul_f32 v[100:101], v[100:101], v[162:163] op_sel_hi:[1,0]
	v_cvt_pk_bf16_f32 v118, v112, v113
	v_add_f32_e32 v143, 1.0, v143
	v_rcp_f32_e32 v171, v143
	v_mov_b64_e32 v[112:113], s[30:31]
	v_mad_i64_i32 v[120:121], s[20:21], v142, s4, v[112:113]
	v_pk_mul_f32 v[122:123], v[122:123], v[170:171]
	v_pk_mul_f32 v[96:97], v[96:97], v[162:163] op_sel_hi:[1,0]
	v_pk_mul_f32 v[114:115], v[114:115], v[122:123]
	v_pk_mul_f32 v[98:99], v[98:99], v[162:163] op_sel_hi:[1,0]
	v_cvt_pk_bf16_f32 v119, v114, v115
	v_lshlrev_b64 v[114:115], 1, v[164:165]
	v_lshl_add_u64 v[120:121], v[120:121], 0, v[114:115]
	flat_store_dwordx4 v[120:121], v[116:119]
	v_or_b32_e32 v120, 16, v142
	v_pk_mul_f32 v[102:103], v[102:103], v[162:163] op_sel_hi:[1,0]
	v_mul_f32_e32 v116, 0xbfb8aa3b, v108
	v_mul_f32_e32 v117, 0xbfb8aa3b, v109
	v_mul_f32_e32 v118, 0xbfb8aa3b, v110
	v_mul_f32_e32 v119, 0xbfb8aa3b, v111
	v_exp_f32_e32 v116, v116
	v_exp_f32_e32 v117, v117
	v_exp_f32_e32 v118, v118
	v_exp_f32_e32 v119, v119
	v_add_f32_e32 v116, 1.0, v116
	v_add_f32_e32 v117, 1.0, v117
	v_add_f32_e32 v118, 1.0, v118
	v_add_f32_e32 v119, 1.0, v119
	v_rcp_f32_e32 v116, v116
	v_rcp_f32_e32 v117, v117
	v_rcp_f32_e32 v118, v118
	v_rcp_f32_e32 v119, v119
	v_pk_mul_f32 v[94:95], v[94:95], v[160:161] op_sel_hi:[1,0]
	v_pk_mul_f32 v[108:109], v[108:109], v[116:117]
	v_mul_f32_e32 v116, 0xbfb8aa3b, v104
	v_pk_mul_f32 v[110:111], v[110:111], v[118:119]
	v_mul_f32_e32 v117, 0xbfb8aa3b, v105
	v_mul_f32_e32 v118, 0xbfb8aa3b, v106
	v_mul_f32_e32 v119, 0xbfb8aa3b, v107
	v_exp_f32_e32 v116, v116
	v_exp_f32_e32 v117, v117
	v_exp_f32_e32 v118, v118
	v_exp_f32_e32 v119, v119
	v_add_f32_e32 v116, 1.0, v116
	v_add_f32_e32 v117, 1.0, v117
	v_add_f32_e32 v118, 1.0, v118
	v_add_f32_e32 v119, 1.0, v119
	v_rcp_f32_e32 v116, v116
	v_rcp_f32_e32 v117, v117
	v_rcp_f32_e32 v118, v118
	v_rcp_f32_e32 v119, v119
	v_pk_mul_f32 v[100:101], v[100:101], v[108:109]
	v_pk_mul_f32 v[104:105], v[104:105], v[116:117]
	v_pk_mul_f32 v[102:103], v[102:103], v[110:111]
	v_pk_mul_f32 v[106:107], v[106:107], v[118:119]
	v_pk_mul_f32 v[92:93], v[92:93], v[160:161] op_sel_hi:[1,0]
	v_pk_mul_f32 v[106:107], v[98:99], v[106:107]
	v_pk_mul_f32 v[98:99], v[96:97], v[104:105]
	v_cvt_pk_bf16_f32 v96, v100, v101
	v_mad_i64_i32 v[100:101], s[20:21], v120, s4, v[112:113]
	v_cvt_pk_bf16_f32 v97, v102, v103
	v_cvt_pk_bf16_f32 v98, v98, v99
	v_cvt_pk_bf16_f32 v99, v106, v107
; __device__ __forceinline__ unsigned cvt_pk_bf16(float lo, float hi) { unsigned r; asm volatile("v_cvt_pk_bf16_f32 %0, %1, %2" : "=v"(r) : "v"(lo), "v"(hi)); return r; }
; __device__ __forceinline__ float silu1(float v) { return v * __builtin_amdgcn_rcpf(1.0f + __builtin_amdgcn_exp2f(-1.4426950408889634f * v)); }
; __device__ __forceinline__ f32x4 silu4(f32x4 v) { return (f32x4){silu1(v[0]), silu1(v[1]), silu1(v[2]), silu1(v[3])}; }
; __device__ __forceinline__ u32x4 pack8(f32x4 v0, f32x4 v1) { u32x4 w; w.x = cvt_pk_bf16(v0[0], v0[1]); w.y = cvt_pk_bf16(v0[2], v0[3]); w.z = cvt_pk_bf16(v1[0], v1[1]); w.w = cvt_pk_bf16(v1[2], v1[3]); return w; }
;     __device__ __forceinline__ void operator()(const f32x4 (&acc)[2][2][4][2], const Unit& u, int wr, int wc, int fr, int fq, const Pre& pre) const {
;     ...
;         for (int ai = 0; ai < 2; ++ai)
; #pragma unroll
;             for (int m = 0; m < 4; ++m) { const int row = row0 + ai * HALF + m * 16; const float r = rs8[ai * 4 + m];
;                 const f32x4 g0 = silu4(acc[ai][0][m][0] * r), g1 = silu4(acc[ai][0][m][1] * r);
;                 const f32x4 v0 = g0 * (acc[ai][1][m][0] * r), v1 = g1 * (acc[ai][1][m][1] * r);
;                 *(u32x4*)(O + (size_t)row * 2816 + col0) = pack8(v0, v1); }
	v_lshl_add_u64 v[100:101], v[100:101], 0, v[114:115]
	flat_store_dwordx4 v[100:101], v[96:99]
	v_pk_mul_f32 v[90:91], v[90:91], v[160:161] op_sel_hi:[1,0]
	v_pk_mul_f32 v[88:89], v[88:89], v[160:161] op_sel_hi:[1,0]
	v_mul_f32_e32 v96, 0xbfb8aa3b, v92
	v_mul_f32_e32 v97, 0xbfb8aa3b, v93
	v_mul_f32_e32 v98, 0xbfb8aa3b, v94
	v_mul_f32_e32 v99, 0xbfb8aa3b, v95
	v_exp_f32_e32 v96, v96
	v_exp_f32_e32 v97, v97
	v_exp_f32_e32 v98, v98
	v_exp_f32_e32 v99, v99
	v_add_f32_e32 v96, 1.0, v96
	v_add_f32_e32 v97, 1.0, v97
	v_add_f32_e32 v98, 1.0, v98
	v_add_f32_e32 v99, 1.0, v99
	v_rcp_f32_e32 v96, v96
	v_rcp_f32_e32 v97, v97
	v_rcp_f32_e32 v98, v98
	v_rcp_f32_e32 v99, v99
	ds_bpermute_b32 v158, v147, v146 offset:64
	v_pk_mul_f32 v[92:93], v[92:93], v[96:97]
	v_mul_f32_e32 v96, 0xbfb8aa3b, v88
	v_pk_mul_f32 v[94:95], v[94:95], v[98:99]
	v_mul_f32_e32 v97, 0xbfb8aa3b, v89
	v_mul_f32_e32 v98, 0xbfb8aa3b, v90
	v_mul_f32_e32 v99, 0xbfb8aa3b, v91
	v_exp_f32_e32 v96, v96
	v_exp_f32_e32 v97, v97
	v_exp_f32_e32 v98, v98
	v_exp_f32_e32 v99, v99
	v_add_f32_e32 v96, 1.0, v96
	v_add_f32_e32 v97, 1.0, v97
	v_add_f32_e32 v98, 1.0, v98
	v_add_f32_e32 v99, 1.0, v99
	v_rcp_f32_e32 v96, v96
	v_rcp_f32_e32 v97, v97
	v_rcp_f32_e32 v98, v98
	v_rcp_f32_e32 v99, v99
	v_pk_mul_f32 v[84:85], v[84:85], v[160:161] op_sel_hi:[1,0]
	v_or_b32_e32 v100, 32, v142
	v_pk_mul_f32 v[88:89], v[88:89], v[96:97]
	v_pk_mul_f32 v[90:91], v[90:91], v[98:99]
	v_pk_mul_f32 v[84:85], v[84:85], v[92:93]
	v_pk_mul_f32 v[80:81], v[80:81], v[160:161] op_sel_hi:[1,0]
	v_pk_mul_f32 v[82:83], v[82:83], v[160:161] op_sel_hi:[1,0]
	v_pk_mul_f32 v[86:87], v[86:87], v[160:161] op_sel_hi:[1,0]
	v_pk_mul_f32 v[90:91], v[82:83], v[90:91]
	v_pk_mul_f32 v[82:83], v[80:81], v[88:89]
	v_cvt_pk_bf16_f32 v80, v84, v85
	v_mad_i64_i32 v[84:85], s[20:21], v100, s4, v[112:113]
	v_pk_mul_f32 v[86:87], v[86:87], v[94:95]
	v_lshl_add_u64 v[84:85], v[84:85], 0, v[114:115]
	v_cvt_pk_bf16_f32 v81, v86, v87
	v_cvt_pk_bf16_f32 v82, v82, v83
	v_cvt_pk_bf16_f32 v83, v90, v91
	s_waitcnt lgkmcnt(0)
	v_pk_mul_f32 v[78:79], v[78:79], v[158:159] op_sel_hi:[1,0]
	v_pk_mul_f32 v[76:77], v[76:77], v[158:159] op_sel_hi:[1,0]
	flat_store_dwordx4 v[84:85], v[80:83]
	v_pk_mul_f32 v[74:75], v[74:75], v[158:159] op_sel_hi:[1,0]
	v_pk_mul_f32 v[72:73], v[72:73], v[158:159] op_sel_hi:[1,0]
	v_mul_f32_e32 v80, 0xbfb8aa3b, v76
	v_mul_f32_e32 v81, 0xbfb8aa3b, v77
	v_mul_f32_e32 v82, 0xbfb8aa3b, v78
	v_mul_f32_e32 v83, 0xbfb8aa3b, v79
	v_exp_f32_e32 v80, v80
	v_exp_f32_e32 v81, v81
	v_exp_f32_e32 v82, v82
	v_exp_f32_e32 v83, v83
	v_add_f32_e32 v80, 1.0, v80
	v_add_f32_e32 v81, 1.0, v81
	v_add_f32_e32 v82, 1.0, v82
	v_add_f32_e32 v83, 1.0, v83
	v_rcp_f32_e32 v80, v80
	v_rcp_f32_e32 v81, v81
	v_rcp_f32_e32 v82, v82
	v_rcp_f32_e32 v83, v83
	v_pk_mul_f32 v[68:69], v[68:69], v[158:159] op_sel_hi:[1,0]
	v_pk_mul_f32 v[76:77], v[76:77], v[80:81]
	v_mul_f32_e32 v80, 0xbfb8aa3b, v72
	v_pk_mul_f32 v[78:79], v[78:79], v[82:83]
	v_mul_f32_e32 v81, 0xbfb8aa3b, v73
	v_mul_f32_e32 v82, 0xbfb8aa3b, v74
	v_mul_f32_e32 v83, 0xbfb8aa3b, v75
	v_exp_f32_e32 v80, v80
	v_exp_f32_e32 v81, v81
	v_exp_f32_e32 v82, v82
	v_exp_f32_e32 v83, v83
	v_add_f32_e32 v80, 1.0, v80
	v_add_f32_e32 v81, 1.0, v81
	v_add_f32_e32 v82, 1.0, v82
	v_add_f32_e32 v83, 1.0, v83
	v_rcp_f32_e32 v80, v80
	v_rcp_f32_e32 v81, v81
	v_rcp_f32_e32 v82, v82
	v_rcp_f32_e32 v83, v83
	v_or_b32_e32 v84, 48, v142
	v_pk_mul_f32 v[72:73], v[72:73], v[80:81]
	v_pk_mul_f32 v[68:69], v[68:69], v[76:77]
	v_pk_mul_f32 v[74:75], v[74:75], v[82:83]
	v_pk_mul_f32 v[64:65], v[64:65], v[158:159] op_sel_hi:[1,0]
	v_pk_mul_f32 v[66:67], v[66:67], v[158:159] op_sel_hi:[1,0]
	v_pk_mul_f32 v[70:71], v[70:71], v[158:159] op_sel_hi:[1,0]
	v_pk_mul_f32 v[74:75], v[66:67], v[74:75]
	v_pk_mul_f32 v[66:67], v[64:65], v[72:73]
	v_cvt_pk_bf16_f32 v64, v68, v69
	v_mad_i64_i32 v[68:69], s[20:21], v84, s4, v[112:113]
	v_pk_mul_f32 v[70:71], v[70:71], v[78:79]
	v_lshl_add_u64 v[68:69], v[68:69], 0, v[114:115]
	v_cvt_pk_bf16_f32 v65, v70, v71
	v_cvt_pk_bf16_f32 v66, v66, v67
	v_cvt_pk_bf16_f32 v67, v74, v75
	v_pk_mul_f32 v[62:63], v[62:63], v[156:157] op_sel_hi:[1,0]
	v_pk_mul_f32 v[60:61], v[60:61], v[156:157] op_sel_hi:[1,0]
	flat_store_dwordx4 v[68:69], v[64:67]
	v_pk_mul_f32 v[58:59], v[58:59], v[156:157] op_sel_hi:[1,0]
	v_pk_mul_f32 v[56:57], v[56:57], v[156:157] op_sel_hi:[1,0]
	v_mul_f32_e32 v64, 0xbfb8aa3b, v60
	v_mul_f32_e32 v65, 0xbfb8aa3b, v61
	v_mul_f32_e32 v66, 0xbfb8aa3b, v62
	v_mul_f32_e32 v67, 0xbfb8aa3b, v63
	v_exp_f32_e32 v64, v64
	v_exp_f32_e32 v65, v65
	v_exp_f32_e32 v66, v66
	v_exp_f32_e32 v67, v67
	v_add_f32_e32 v64, 1.0, v64
	v_add_f32_e32 v65, 1.0, v65
	v_add_f32_e32 v66, 1.0, v66
	v_add_f32_e32 v67, 1.0, v67
	v_rcp_f32_e32 v64, v64
	v_rcp_f32_e32 v65, v65
	v_rcp_f32_e32 v66, v66
	v_rcp_f32_e32 v67, v67
	ds_bpermute_b32 v154, v147, v146 offset:128
	v_pk_mul_f32 v[60:61], v[60:61], v[64:65]
	v_mul_f32_e32 v64, 0xbfb8aa3b, v56
	v_pk_mul_f32 v[62:63], v[62:63], v[66:67]
	v_mul_f32_e32 v65, 0xbfb8aa3b, v57
	v_mul_f32_e32 v66, 0xbfb8aa3b, v58
	v_mul_f32_e32 v67, 0xbfb8aa3b, v59
	v_exp_f32_e32 v64, v64
	v_exp_f32_e32 v65, v65
	v_exp_f32_e32 v66, v66
	v_exp_f32_e32 v67, v67
	v_add_f32_e32 v64, 1.0, v64
	v_add_f32_e32 v65, 1.0, v65
	v_add_f32_e32 v66, 1.0, v66
	v_add_f32_e32 v67, 1.0, v67
	v_rcp_f32_e32 v64, v64
	v_rcp_f32_e32 v65, v65
	v_rcp_f32_e32 v66, v66
	v_rcp_f32_e32 v67, v67
	v_pk_mul_f32 v[52:53], v[52:53], v[156:157] op_sel_hi:[1,0]
	v_add_u32_e32 v68, 0x80, v142
	v_pk_mul_f32 v[56:57], v[56:57], v[64:65]
	v_pk_mul_f32 v[58:59], v[58:59], v[66:67]
	v_pk_mul_f32 v[52:53], v[52:53], v[60:61]
	v_pk_mul_f32 v[48:49], v[48:49], v[156:157] op_sel_hi:[1,0]
	v_pk_mul_f32 v[50:51], v[50:51], v[156:157] op_sel_hi:[1,0]
	v_pk_mul_f32 v[54:55], v[54:55], v[156:157] op_sel_hi:[1,0]
	v_pk_mul_f32 v[58:59], v[50:51], v[58:59]
	v_pk_mul_f32 v[50:51], v[48:49], v[56:57]
	v_cvt_pk_bf16_f32 v48, v52, v53
	v_mad_i64_i32 v[52:53], s[20:21], v68, s4, v[112:113]
	v_pk_mul_f32 v[54:55], v[54:55], v[62:63]
	v_lshl_add_u64 v[52:53], v[52:53], 0, v[114:115]
	v_cvt_pk_bf16_f32 v49, v54, v55
	v_cvt_pk_bf16_f32 v50, v50, v51
	v_cvt_pk_bf16_f32 v51, v58, v59
	s_waitcnt lgkmcnt(0)
; __device__ __forceinline__ f32x4 silu4(f32x4 v) { return (f32x4){silu1(v[0]), silu1(v[1]), silu1(v[2]), silu1(v[3])}; }
; __device__ __forceinline__ u32x4 pack8(f32x4 v0, f32x4 v1) { u32x4 w; w.x = cvt_pk_bf16(v0[0], v0[1]); w.y = cvt_pk_bf16(v0[2], v0[3]); w.z = cvt_pk_bf16(v1[0], v1[1]); w.w = cvt_pk_bf16(v1[2], v1[3]); return w; }
; #define PG8_BAR __builtin_amdgcn_s_barrier()
;     __device__ __forceinline__ void operator()(const f32x4 (&acc)[2][2][4][2], const Unit& u, int wr, int wc, int fr, int fq, const Pre& pre) const {
;     ...
;         for (int ai = 0; ai < 2; ++ai)
; #pragma unroll
;             for (int m = 0; m < 4; ++m) { const int row = row0 + ai * HALF + m * 16; const float r = rs8[ai * 4 + m];
;                 const f32x4 g0 = silu4(acc[ai][0][m][0] * r), g1 = silu4(acc[ai][0][m][1] * r);
;                 const f32x4 v0 = g0 * (acc[ai][1][m][0] * r), v1 = g1 * (acc[ai][1][m][1] * r);
;                 *(u32x4*)(O + (size_t)row * 2816 + col0) = pack8(v0, v1); }
; template <class Epi, class Sched, bool ALIGN_EPI = false, bool SP2 = false>
; __device__ __forceinline__ void gemm_phase(PG8_LAS unsigned char* lds, const Gemm g, const Sched& S, const Epi& E) {
;     ...
;         if constexpr (ALIGN_EPI) { if (wr == 0) PG8_BAR; }
;         if constexpr (!Epi::AFTER_DRAIN) { E(acc, cur, wr, wc, fr, fq, pre); S.done(cur); }
;         if (!has_next) break;
; #pragma unroll
;         for (int a = 0; a < 2; ++a)
; #pragma unroll
;             for (int b = 0; b < 2; ++b)
; #pragma unroll
;                 for (int m = 0; m < 4; ++m)
; #pragma unroll
;                     for (int n = 0; n < 2; ++n) acc[a][b][m][n] = (f32x4){0.f, 0.f, 0.f, 0.f};
;         cur = nxt; cA = nA; cB = nB; ++ui;
;         if constexpr (ALIGN_EPI) { if (wr == 1) PG8_BAR; }
	v_pk_mul_f32 v[46:47], v[46:47], v[154:155] op_sel_hi:[1,0]
	v_pk_mul_f32 v[44:45], v[44:45], v[154:155] op_sel_hi:[1,0]
	flat_store_dwordx4 v[52:53], v[48:51]
	v_pk_mul_f32 v[42:43], v[42:43], v[154:155] op_sel_hi:[1,0]
	v_pk_mul_f32 v[40:41], v[40:41], v[154:155] op_sel_hi:[1,0]
	v_mul_f32_e32 v48, 0xbfb8aa3b, v44
	v_mul_f32_e32 v49, 0xbfb8aa3b, v45
	v_mul_f32_e32 v50, 0xbfb8aa3b, v46
	v_mul_f32_e32 v51, 0xbfb8aa3b, v47
	v_exp_f32_e32 v48, v48
	v_exp_f32_e32 v49, v49
	v_exp_f32_e32 v50, v50
	v_exp_f32_e32 v51, v51
	v_add_f32_e32 v48, 1.0, v48
	v_add_f32_e32 v49, 1.0, v49
	v_add_f32_e32 v50, 1.0, v50
	v_add_f32_e32 v51, 1.0, v51
	v_rcp_f32_e32 v48, v48
	v_rcp_f32_e32 v49, v49
	v_rcp_f32_e32 v50, v50
	v_rcp_f32_e32 v51, v51
	v_pk_mul_f32 v[36:37], v[36:37], v[154:155] op_sel_hi:[1,0]
	v_pk_mul_f32 v[44:45], v[44:45], v[48:49]
	v_mul_f32_e32 v48, 0xbfb8aa3b, v40
	v_pk_mul_f32 v[46:47], v[46:47], v[50:51]
	v_mul_f32_e32 v49, 0xbfb8aa3b, v41
	v_mul_f32_e32 v50, 0xbfb8aa3b, v42
	v_mul_f32_e32 v51, 0xbfb8aa3b, v43
	v_exp_f32_e32 v48, v48
	v_exp_f32_e32 v49, v49
	v_exp_f32_e32 v50, v50
	v_exp_f32_e32 v51, v51
	v_add_f32_e32 v48, 1.0, v48
	v_add_f32_e32 v49, 1.0, v49
	v_add_f32_e32 v50, 1.0, v50
	v_add_f32_e32 v51, 1.0, v51
	v_rcp_f32_e32 v48, v48
	v_rcp_f32_e32 v49, v49
	v_rcp_f32_e32 v50, v50
	v_rcp_f32_e32 v51, v51
	v_add_u32_e32 v52, 0x90, v142
	v_pk_mul_f32 v[40:41], v[40:41], v[48:49]
	v_pk_mul_f32 v[36:37], v[36:37], v[44:45]
	v_pk_mul_f32 v[42:43], v[42:43], v[50:51]
	v_pk_mul_f32 v[32:33], v[32:33], v[154:155] op_sel_hi:[1,0]
	v_pk_mul_f32 v[34:35], v[34:35], v[154:155] op_sel_hi:[1,0]
	v_pk_mul_f32 v[38:39], v[38:39], v[154:155] op_sel_hi:[1,0]
	v_pk_mul_f32 v[42:43], v[34:35], v[42:43]
	v_pk_mul_f32 v[34:35], v[32:33], v[40:41]
	v_cvt_pk_bf16_f32 v32, v36, v37
	v_mad_i64_i32 v[36:37], s[20:21], v52, s4, v[112:113]
	v_pk_mul_f32 v[38:39], v[38:39], v[46:47]
	v_lshl_add_u64 v[36:37], v[36:37], 0, v[114:115]
	v_cvt_pk_bf16_f32 v33, v38, v39
	v_cvt_pk_bf16_f32 v34, v34, v35
	v_cvt_pk_bf16_f32 v35, v42, v43
	v_pk_mul_f32 v[30:31], v[30:31], v[152:153] op_sel_hi:[1,0]
	v_pk_mul_f32 v[28:29], v[28:29], v[152:153] op_sel_hi:[1,0]
	flat_store_dwordx4 v[36:37], v[32:35]
	v_pk_mul_f32 v[26:27], v[26:27], v[152:153] op_sel_hi:[1,0]
	v_pk_mul_f32 v[24:25], v[24:25], v[152:153] op_sel_hi:[1,0]
	v_mul_f32_e32 v32, 0xbfb8aa3b, v28
	v_mul_f32_e32 v33, 0xbfb8aa3b, v29
	v_mul_f32_e32 v34, 0xbfb8aa3b, v30
	v_mul_f32_e32 v35, 0xbfb8aa3b, v31
	v_exp_f32_e32 v32, v32
	v_exp_f32_e32 v33, v33
	v_exp_f32_e32 v34, v34
	v_exp_f32_e32 v35, v35
	v_add_f32_e32 v32, 1.0, v32
	v_add_f32_e32 v33, 1.0, v33
	v_add_f32_e32 v34, 1.0, v34
	v_add_f32_e32 v35, 1.0, v35
	v_rcp_f32_e32 v32, v32
	v_rcp_f32_e32 v33, v33
	v_rcp_f32_e32 v34, v34
	v_rcp_f32_e32 v35, v35
	ds_bpermute_b32 v146, v147, v146 offset:192
	v_pk_mul_f32 v[28:29], v[28:29], v[32:33]
	v_mul_f32_e32 v32, 0xbfb8aa3b, v24
	v_pk_mul_f32 v[30:31], v[30:31], v[34:35]
	v_mul_f32_e32 v33, 0xbfb8aa3b, v25
	v_mul_f32_e32 v34, 0xbfb8aa3b, v26
	v_mul_f32_e32 v35, 0xbfb8aa3b, v27
	v_exp_f32_e32 v32, v32
	v_exp_f32_e32 v33, v33
	v_exp_f32_e32 v34, v34
	v_exp_f32_e32 v35, v35
	v_add_f32_e32 v32, 1.0, v32
	v_add_f32_e32 v33, 1.0, v33
	v_add_f32_e32 v34, 1.0, v34
	v_add_f32_e32 v35, 1.0, v35
	v_rcp_f32_e32 v32, v32
	v_rcp_f32_e32 v33, v33
	v_rcp_f32_e32 v34, v34
	v_rcp_f32_e32 v35, v35
	v_pk_mul_f32 v[20:21], v[20:21], v[152:153] op_sel_hi:[1,0]
	v_add_u32_e32 v36, 0xa0, v142
	v_pk_mul_f32 v[24:25], v[24:25], v[32:33]
	v_pk_mul_f32 v[26:27], v[26:27], v[34:35]
	v_pk_mul_f32 v[20:21], v[20:21], v[28:29]
	v_pk_mul_f32 v[16:17], v[16:17], v[152:153] op_sel_hi:[1,0]
	v_pk_mul_f32 v[18:19], v[18:19], v[152:153] op_sel_hi:[1,0]
	v_pk_mul_f32 v[22:23], v[22:23], v[152:153] op_sel_hi:[1,0]
	v_pk_mul_f32 v[26:27], v[18:19], v[26:27]
	v_pk_mul_f32 v[18:19], v[16:17], v[24:25]
	v_cvt_pk_bf16_f32 v16, v20, v21
	v_mad_i64_i32 v[20:21], s[20:21], v36, s4, v[112:113]
	v_pk_mul_f32 v[22:23], v[22:23], v[30:31]
	v_lshl_add_u64 v[20:21], v[20:21], 0, v[114:115]
	v_cvt_pk_bf16_f32 v17, v22, v23
	v_cvt_pk_bf16_f32 v18, v18, v19
	v_cvt_pk_bf16_f32 v19, v26, v27
	s_waitcnt lgkmcnt(0)
	v_pk_mul_f32 v[14:15], v[14:15], v[146:147] op_sel_hi:[1,0]
	v_pk_mul_f32 v[12:13], v[12:13], v[146:147] op_sel_hi:[1,0]
	flat_store_dwordx4 v[20:21], v[16:19]
	v_pk_mul_f32 v[10:11], v[10:11], v[146:147] op_sel_hi:[1,0]
	v_pk_mul_f32 v[8:9], v[8:9], v[146:147] op_sel_hi:[1,0]
	v_mul_f32_e32 v16, 0xbfb8aa3b, v12
	v_mul_f32_e32 v17, 0xbfb8aa3b, v13
	v_mul_f32_e32 v18, 0xbfb8aa3b, v14
	v_mul_f32_e32 v19, 0xbfb8aa3b, v15
	v_exp_f32_e32 v16, v16
	v_exp_f32_e32 v17, v17
	v_exp_f32_e32 v18, v18
	v_exp_f32_e32 v19, v19
	v_add_f32_e32 v16, 1.0, v16
	v_add_f32_e32 v17, 1.0, v17
	v_add_f32_e32 v18, 1.0, v18
	v_add_f32_e32 v19, 1.0, v19
	v_rcp_f32_e32 v16, v16
	v_rcp_f32_e32 v17, v17
	v_rcp_f32_e32 v18, v18
	v_rcp_f32_e32 v19, v19
	v_pk_mul_f32 v[4:5], v[4:5], v[146:147] op_sel_hi:[1,0]
	v_pk_mul_f32 v[12:13], v[12:13], v[16:17]
	v_mul_f32_e32 v16, 0xbfb8aa3b, v8
	v_pk_mul_f32 v[14:15], v[14:15], v[18:19]
	v_mul_f32_e32 v17, 0xbfb8aa3b, v9
	v_mul_f32_e32 v18, 0xbfb8aa3b, v10
	v_mul_f32_e32 v19, 0xbfb8aa3b, v11
	v_exp_f32_e32 v16, v16
	v_exp_f32_e32 v17, v17
	v_exp_f32_e32 v18, v18
	v_exp_f32_e32 v19, v19
	v_add_f32_e32 v16, 1.0, v16
	v_add_f32_e32 v17, 1.0, v17
	v_add_f32_e32 v18, 1.0, v18
	v_add_f32_e32 v19, 1.0, v19
	v_rcp_f32_e32 v16, v16
	v_rcp_f32_e32 v17, v17
	v_rcp_f32_e32 v18, v18
	v_rcp_f32_e32 v19, v19
	v_add_u32_e32 v20, 0xb0, v142
	v_pk_mul_f32 v[8:9], v[8:9], v[16:17]
	v_pk_mul_f32 v[4:5], v[4:5], v[12:13]
	v_pk_mul_f32 v[10:11], v[10:11], v[18:19]
	v_pk_mul_f32 v[0:1], v[0:1], v[146:147] op_sel_hi:[1,0]
	v_pk_mul_f32 v[2:3], v[2:3], v[146:147] op_sel_hi:[1,0]
	v_pk_mul_f32 v[6:7], v[6:7], v[146:147] op_sel_hi:[1,0]
	v_pk_mul_f32 v[10:11], v[2:3], v[10:11]
	v_pk_mul_f32 v[2:3], v[0:1], v[8:9]
	v_cvt_pk_bf16_f32 v0, v4, v5
	v_mad_i64_i32 v[4:5], s[20:21], v20, s4, v[112:113]
	v_lshl_add_u64 v[4:5], v[4:5], 0, v[114:115]
	s_mov_b64 s[26:27], -1
	s_andn2_b64 vcc, exec, s[40:41]
	v_pk_mul_f32 v[6:7], v[6:7], v[14:15]
	s_nop 0
	v_cvt_pk_bf16_f32 v1, v6, v7
	v_cvt_pk_bf16_f32 v2, v2, v3
	v_cvt_pk_bf16_f32 v3, v10, v11
	flat_store_dwordx4 v[4:5], v[0:3]
	s_cbranch_vccnz .LBB0_148
	s_andn2_b64 vcc, exec, s[44:45]
	s_cbranch_vccnz .LBB0_147
	s_barrier
	s_branch .LBB0_147

; __device__ __forceinline__ float ss2f(unsigned long long v) { return (float)v * (1.0f / 16777216.0f); }
; __device__ __forceinline__ void rstd8(float (&r)[8], const PreSS& p, int fr) {
;     const float a = __builtin_amdgcn_rsqf(ss2f(p.v0) * (1.0f / 1024.0f) + RMS_EPS), b = __builtin_amdgcn_rsqf(ss2f(p.v1) * (1.0f / 1024.0f) + RMS_EPS);
; #pragma unroll
;     for (int k = 0; k < 8; ++k) r[k] = __shfl((k & 1) ? b : a, fr + 16 * (k >> 1));
; }
;     __device__ __forceinline__ void operator()(const f32x4 (&acc)[2][2][4][2], const Unit& u, int wr, int wc, int fr, int fq, const Pre& pre) const {
;         const int row0 = u.pm * BM + wr * 64 + fr, col0 = u.pn * BM + wc * 32 + 8 * fq;
;         float rs8[8]; rstd8(rs8, pre, fr);
;         if (u.pn == 2 || u.pn == 3) {
.LBB0_417:
	s_waitcnt vmcnt(8)
	v_ffbh_u32_e32 v154, v147
	v_min_u32_e32 v154, 32, v154
	v_lshlrev_b64 v[146:147], v154, v[146:147]
	v_min_u32_e32 v146, 1, v146
	v_or_b32_e32 v146, v147, v146
	v_ffbh_u32_e32 v147, v143
	v_min_u32_e32 v147, 32, v147
	v_cvt_f32_u32_e32 v146, v146
	v_lshlrev_b64 v[142:143], v147, v[142:143]
	v_min_u32_e32 v142, 1, v142
	v_or_b32_e32 v142, v143, v142
	v_sub_u32_e32 v154, 32, v154
	v_cvt_f32_u32_e32 v142, v142
	v_ldexp_f32 v146, v146, v154
	v_mul_f32_e32 v146, 0x33800000, v146
	v_fmamk_f32 v143, v146, 0x3a800000, v233
	v_sub_u32_e32 v146, 32, v147
	v_ldexp_f32 v142, v142, v146
	v_mul_f32_e32 v142, 0x33800000, v142
	v_fmamk_f32 v142, v142, 0x3a800000, v233
	v_rsq_f32_e32 v143, v143
	v_rsq_f32_e32 v142, v142
	v_and_or_b32 v146, v236, 64, v145
	v_lshlrev_b32_e32 v147, 2, v146
	ds_bpermute_b32 v164, v147, v143
	ds_bpermute_b32 v162, v147, v142
	ds_bpermute_b32 v160, v147, v143 offset:64
	ds_bpermute_b32 v158, v147, v142 offset:64
	ds_bpermute_b32 v156, v147, v143 offset:128
	ds_bpermute_b32 v154, v147, v142 offset:128
	ds_bpermute_b32 v146, v147, v143 offset:192
	ds_bpermute_b32 v142, v147, v142 offset:192
	s_and_b32 s4, s68, -2
	s_cmp_eq_u32 s4, 2
	s_mov_b64 s[26:27], -1
	s_cbranch_scc1 .LBB0_419
	s_mov_b64 s[26:27], 0
